# P3 ssd_s2: all 16 chunk states of a chain staged at once through LDS-DMA
# baseline (speedup 1.0000x reference)
.LBB0_448:
	s_or_b64 exec, exec, s[2:3]
	s_and_b32 s2, s59, 1
	s_cmp_eq_u32 s2, 0
	s_cselect_b64 s[6:7], -1, 0
	s_cmp_eq_u32 s2, 1
	s_cselect_b64 s[2:3], -1, 0
	s_and_b64 vcc, exec, s[2:3]
	s_waitcnt lgkmcnt(0)
	s_barrier
	s_cbranch_vccz .LBB0_453
	s_mov_b32 s2, 0x40000
	v_cmp_gt_i32_e32 vcc, s2, v184
	s_and_saveexec_b64 s[2:3], vcc
	s_cbranch_execz .LBB0_452
	s_add_u32 s4, s76, 0x3cc8000
	s_addc_u32 s5, s77, 0
	s_lshl_b32 s12, s58, 9
	s_add_u32 s8, s74, 0x4200000
	s_addc_u32 s9, s75, 0
	s_mov_b64 s[10:11], 0
	s_mov_b32 s28, 0x3ffff
	v_mov_b32_e32 v10, v184
	v_readfirstlane_b32 s20, v0
	v_and_b32_e32 v243, 63, v0
	s_lshr_b32 s20, s20, 6
	s_lshl_b32 s20, s20, 14
	v_lshlrev_b32_e32 v243, 4, v243
	v_add_u32_e32 v243, s20, v243
.Ls2a_loop:
	v_and_b32_e32 v2, 0x7ff, v10
	v_lshlrev_b32_e32 v2, 4, v2
	v_lshrrev_b32_e32 v4, 11, v10
	v_lshl_or_b32 v4, v4, 15, v2
	v_lshrrev_b32_e32 v3, 15, v10
	v_bfe_u32 v244, v10, 11, 4
	v_lshl_or_b32 v2, v244, 15, v2
	v_lshl_or_b32 v2, v3, 23, v2
	v_lshl_or_b32 v3, v3, 8, v244
	v_lshlrev_b32_e32 v3, 2, v3
	s_mov_b64 s[22:23], s[74:75]
	s_mov_b64 s[24:25], s[74:75]
	s_add_i32 m0, s20, 0x0
	s_nop 0
	global_load_lds_dwordx4 v2, s[22:23]
	s_add_u32 s22, s22, 0x80000
	s_addc_u32 s23, s23, 0
	s_add_i32 m0, s20, 0x400
	s_nop 0
	global_load_lds_dwordx4 v2, s[22:23]
	s_add_u32 s22, s22, 0x80000
	s_addc_u32 s23, s23, 0
	s_add_i32 m0, s20, 0x800
	s_nop 0
	global_load_lds_dwordx4 v2, s[22:23]
	s_add_u32 s22, s22, 0x80000
	s_addc_u32 s23, s23, 0
	s_add_i32 m0, s20, 0xc00
	s_nop 0
	global_load_lds_dwordx4 v2, s[22:23]
	s_add_u32 s22, s22, 0x80000
	s_addc_u32 s23, s23, 0
	s_add_i32 m0, s20, 0x1000
	s_nop 0
	global_load_lds_dwordx4 v2, s[22:23]
	s_add_u32 s22, s22, 0x80000
	s_addc_u32 s23, s23, 0
	s_add_i32 m0, s20, 0x1400
	s_nop 0
	global_load_lds_dwordx4 v2, s[22:23]
	s_add_u32 s22, s22, 0x80000
	s_addc_u32 s23, s23, 0
	s_add_i32 m0, s20, 0x1800
	s_nop 0
	global_load_lds_dwordx4 v2, s[22:23]
	s_add_u32 s22, s22, 0x80000
	s_addc_u32 s23, s23, 0
	s_add_i32 m0, s20, 0x1c00
	s_nop 0
	global_load_lds_dwordx4 v2, s[22:23]
	s_add_u32 s22, s22, 0x80000
	s_addc_u32 s23, s23, 0
	s_add_i32 m0, s20, 0x2000
	s_nop 0
	global_load_lds_dwordx4 v2, s[22:23]
	s_add_u32 s22, s22, 0x80000
	s_addc_u32 s23, s23, 0
	s_add_i32 m0, s20, 0x2400
	s_nop 0
	global_load_lds_dwordx4 v2, s[22:23]
	s_add_u32 s22, s22, 0x80000
	s_addc_u32 s23, s23, 0
	s_add_i32 m0, s20, 0x2800
	s_nop 0
	global_load_lds_dwordx4 v2, s[22:23]
	s_add_u32 s22, s22, 0x80000
	s_addc_u32 s23, s23, 0
	s_add_i32 m0, s20, 0x2c00
	s_nop 0
	global_load_lds_dwordx4 v2, s[22:23]
	s_add_u32 s22, s22, 0x80000
	s_addc_u32 s23, s23, 0
	s_add_i32 m0, s20, 0x3000
	s_nop 0
	global_load_lds_dwordx4 v2, s[22:23]
	s_add_u32 s22, s22, 0x80000
	s_addc_u32 s23, s23, 0
	s_add_i32 m0, s20, 0x3400
	s_nop 0
	global_load_lds_dwordx4 v2, s[22:23]
	s_add_u32 s22, s22, 0x80000
	s_addc_u32 s23, s23, 0
	s_add_i32 m0, s20, 0x3800
	s_nop 0
	global_load_lds_dwordx4 v2, s[22:23]
	s_add_u32 s22, s22, 0x80000
	s_addc_u32 s23, s23, 0
	s_add_i32 m0, s20, 0x3c00
	s_nop 0
	global_load_lds_dwordx4 v2, s[22:23]
	s_add_u32 s22, s22, 0x80000
	s_addc_u32 s23, s23, 0
	global_load_dword v5, v3, s[4:5] offset:0
	global_load_dword v6, v3, s[4:5] offset:64
	global_load_dword v7, v3, s[4:5] offset:128
	global_load_dword v8, v3, s[4:5] offset:192
	global_load_dword v9, v3, s[4:5] offset:256
	global_load_dword v11, v3, s[4:5] offset:320
	global_load_dword v16, v3, s[4:5] offset:384
	global_load_dword v17, v3, s[4:5] offset:448
	global_load_dword v18, v3, s[4:5] offset:512
	global_load_dword v19, v3, s[4:5] offset:576
	global_load_dword v36, v3, s[4:5] offset:640
	global_load_dword v37, v3, s[4:5] offset:704
	global_load_dword v252, v3, s[4:5] offset:768
	global_load_dword v253, v3, s[4:5] offset:832
	global_load_dword v254, v3, s[4:5] offset:896
	global_load_dword v255, v3, s[4:5] offset:960
	v_mov_b32_e32 v12, 0
	v_mov_b32_e32 v13, 0
	v_mov_b32_e32 v14, 0
	v_mov_b32_e32 v15, 0
	v_add_u32_e32 v10, s12, v10
	s_waitcnt vmcnt(0)
	ds_read_b128 v[20:23], v243 offset:0
	ds_read_b128 v[24:27], v243 offset:1024
	ds_read_b128 v[28:31], v243 offset:2048
	ds_read_b128 v[32:35], v243 offset:3072
	s_waitcnt lgkmcnt(3)
	global_store_dwordx4 v2, v[12:15], s[24:25]
	s_add_u32 s24, s24, 0x80000
	s_addc_u32 s25, s25, 0
	s_nop 1
	v_fma_f32 v12, v12, v5, v20
	v_fma_f32 v13, v13, v5, v21
	v_fma_f32 v14, v14, v5, v22
	v_fma_f32 v15, v15, v5, v23
	ds_read_b128 v[20:23], v243 offset:4096
	s_waitcnt lgkmcnt(3)
	global_store_dwordx4 v2, v[12:15], s[24:25]
	s_add_u32 s24, s24, 0x80000
	s_addc_u32 s25, s25, 0
	s_nop 1
	v_fma_f32 v12, v12, v6, v24
	v_fma_f32 v13, v13, v6, v25
	v_fma_f32 v14, v14, v6, v26
	v_fma_f32 v15, v15, v6, v27
	ds_read_b128 v[24:27], v243 offset:5120
	s_waitcnt lgkmcnt(3)
	global_store_dwordx4 v2, v[12:15], s[24:25]
	s_add_u32 s24, s24, 0x80000
	s_addc_u32 s25, s25, 0
	s_nop 1
	v_fma_f32 v12, v12, v7, v28
	v_fma_f32 v13, v13, v7, v29
	v_fma_f32 v14, v14, v7, v30
	v_fma_f32 v15, v15, v7, v31
	ds_read_b128 v[28:31], v243 offset:6144
	s_waitcnt lgkmcnt(3)
	global_store_dwordx4 v2, v[12:15], s[24:25]
	s_add_u32 s24, s24, 0x80000
	s_addc_u32 s25, s25, 0
	s_nop 1
	v_fma_f32 v12, v12, v8, v32
	v_fma_f32 v13, v13, v8, v33
	v_fma_f32 v14, v14, v8, v34
	v_fma_f32 v15, v15, v8, v35
	ds_read_b128 v[32:35], v243 offset:7168
	s_waitcnt lgkmcnt(3)
	global_store_dwordx4 v2, v[12:15], s[24:25]
	s_add_u32 s24, s24, 0x80000
	s_addc_u32 s25, s25, 0
	s_nop 1
	v_fma_f32 v12, v12, v9, v20
	v_fma_f32 v13, v13, v9, v21
	v_fma_f32 v14, v14, v9, v22
	v_fma_f32 v15, v15, v9, v23
	ds_read_b128 v[20:23], v243 offset:8192
	s_waitcnt lgkmcnt(3)
	global_store_dwordx4 v2, v[12:15], s[24:25]
	s_add_u32 s24, s24, 0x80000
	s_addc_u32 s25, s25, 0
	s_nop 1
	v_fma_f32 v12, v12, v11, v24
	v_fma_f32 v13, v13, v11, v25
	v_fma_f32 v14, v14, v11, v26
	v_fma_f32 v15, v15, v11, v27
	ds_read_b128 v[24:27], v243 offset:9216
	s_waitcnt lgkmcnt(3)
	global_store_dwordx4 v2, v[12:15], s[24:25]
	s_add_u32 s24, s24, 0x80000
	s_addc_u32 s25, s25, 0
	s_nop 1
	v_fma_f32 v12, v12, v16, v28
	v_fma_f32 v13, v13, v16, v29
	v_fma_f32 v14, v14, v16, v30
	v_fma_f32 v15, v15, v16, v31
	ds_read_b128 v[28:31], v243 offset:10240
	s_waitcnt lgkmcnt(3)
	global_store_dwordx4 v2, v[12:15], s[24:25]
	s_add_u32 s24, s24, 0x80000
	s_addc_u32 s25, s25, 0
	s_nop 1
	v_fma_f32 v12, v12, v17, v32
	v_fma_f32 v13, v13, v17, v33
	v_fma_f32 v14, v14, v17, v34
	v_fma_f32 v15, v15, v17, v35
	ds_read_b128 v[32:35], v243 offset:11264
	s_waitcnt lgkmcnt(3)
	global_store_dwordx4 v2, v[12:15], s[24:25]
	s_add_u32 s24, s24, 0x80000
	s_addc_u32 s25, s25, 0
	s_nop 1
	v_fma_f32 v12, v12, v18, v20
	v_fma_f32 v13, v13, v18, v21
	v_fma_f32 v14, v14, v18, v22
	v_fma_f32 v15, v15, v18, v23
	ds_read_b128 v[20:23], v243 offset:12288
	s_waitcnt lgkmcnt(3)
	global_store_dwordx4 v2, v[12:15], s[24:25]
	s_add_u32 s24, s24, 0x80000
	s_addc_u32 s25, s25, 0
	s_nop 1
	v_fma_f32 v12, v12, v19, v24
	v_fma_f32 v13, v13, v19, v25
	v_fma_f32 v14, v14, v19, v26
	v_fma_f32 v15, v15, v19, v27
	ds_read_b128 v[24:27], v243 offset:13312
	s_waitcnt lgkmcnt(3)
	global_store_dwordx4 v2, v[12:15], s[24:25]
	s_add_u32 s24, s24, 0x80000
	s_addc_u32 s25, s25, 0
	s_nop 1
	v_fma_f32 v12, v12, v36, v28
	v_fma_f32 v13, v13, v36, v29
	v_fma_f32 v14, v14, v36, v30
	v_fma_f32 v15, v15, v36, v31
	ds_read_b128 v[28:31], v243 offset:14336
	s_waitcnt lgkmcnt(3)
	global_store_dwordx4 v2, v[12:15], s[24:25]
	s_add_u32 s24, s24, 0x80000
	s_addc_u32 s25, s25, 0
	s_nop 1
	v_fma_f32 v12, v12, v37, v32
	v_fma_f32 v13, v13, v37, v33
	v_fma_f32 v14, v14, v37, v34
	v_fma_f32 v15, v15, v37, v35
	ds_read_b128 v[32:35], v243 offset:15360
	s_waitcnt lgkmcnt(3)
	global_store_dwordx4 v2, v[12:15], s[24:25]
	s_add_u32 s24, s24, 0x80000
	s_addc_u32 s25, s25, 0
	s_nop 1
	v_fma_f32 v12, v12, v252, v20
	v_fma_f32 v13, v13, v252, v21
	v_fma_f32 v14, v14, v252, v22
	v_fma_f32 v15, v15, v252, v23
	s_waitcnt lgkmcnt(2)
	global_store_dwordx4 v2, v[12:15], s[24:25]
	s_add_u32 s24, s24, 0x80000
	s_addc_u32 s25, s25, 0
	s_nop 1
	v_fma_f32 v12, v12, v253, v24
	v_fma_f32 v13, v13, v253, v25
	v_fma_f32 v14, v14, v253, v26
	v_fma_f32 v15, v15, v253, v27
	s_waitcnt lgkmcnt(1)
	global_store_dwordx4 v2, v[12:15], s[24:25]
	s_add_u32 s24, s24, 0x80000
	s_addc_u32 s25, s25, 0
	s_nop 1
	v_fma_f32 v12, v12, v254, v28
	v_fma_f32 v13, v13, v254, v29
	v_fma_f32 v14, v14, v254, v30
	v_fma_f32 v15, v15, v254, v31
	s_waitcnt lgkmcnt(0)
	global_store_dwordx4 v2, v[12:15], s[24:25]
	s_add_u32 s24, s24, 0x80000
	s_addc_u32 s25, s25, 0
	s_nop 1
	v_fma_f32 v12, v12, v255, v32
	v_fma_f32 v13, v13, v255, v33
	v_fma_f32 v14, v14, v255, v34
	v_fma_f32 v15, v15, v255, v35
	s_nop 0
	global_store_dwordx4 v4, v[12:15], s[8:9]
	v_cmp_lt_i32_e32 vcc, s28, v10
	s_or_b64 s[10:11], vcc, s[10:11]
	s_andn2_b64 exec, exec, s[10:11]
	s_cbranch_execnz .Ls2a_loop
.LBB0_452:
	s_or_b64 exec, exec, s[2:3]
	s_waitcnt lgkmcnt(0)
	s_barrier

.LBB0_470:
	s_and_b64 vcc, exec, s[6:7]
	s_cbranch_vccz .LBB0_475
	s_waitcnt lgkmcnt(0)
	s_barrier
	s_mov_b32 s2, 0x40000
	v_cmp_gt_i32_e32 vcc, s2, v184
	s_and_saveexec_b64 s[2:3], vcc
	s_cbranch_execz .LBB0_474
	s_add_u32 s4, s76, 0x3cc8000
	s_addc_u32 s5, s77, 0
	s_lshl_b32 s12, s58, 9
	s_add_u32 s8, s74, 0x4200000
	s_addc_u32 s9, s75, 0
	s_mov_b64 s[10:11], 0
	s_mov_b32 s28, 0x3ffff
	v_mov_b32_e32 v10, v184
	v_readfirstlane_b32 s20, v0
	v_and_b32_e32 v243, 63, v0
	s_lshr_b32 s20, s20, 6
	s_lshl_b32 s20, s20, 14
	v_lshlrev_b32_e32 v243, 4, v243
	v_add_u32_e32 v243, s20, v243
